# P5 gate-up epilogue: removed 128 dead DPP-init v_mov and folded 128 redundant seqstart selects (on top of attention epilogue rewrite)
# speedup vs baseline: 1.0087x; 1.0054x over previous
.LBB0_661:
	v_fmamk_f32 v168, v168, 0x39800000, v191
	v_rsq_f32_e32 v182, v168
	v_lshlrev_b32_e32 v168, 5, v181
	s_ashr_i32 s60, s12, 5
	v_and_b32_e32 v168, 0x1e0, v168
	v_mul_f32_e32 v225, v156, v182
	v_mul_f32_e32 v229, v157, v182
	v_mul_f32_e32 v231, v158, v182
	v_mul_f32_e32 v234, v159, v182
	v_mul_f32_e32 v235, v152, v182
	v_mul_f32_e32 v153, v153, v182
	v_mul_f32_e32 v239, v154, v182
	v_mul_f32_e32 v240, v155, v182
	v_and_b32_e32 v241, 0xfff, v181
	v_cmp_le_i32_e64 s[12:13], s53, v181
	v_cmp_gt_i32_e64 s[14:15], s73, v181
	s_ashr_i32 s61, s60, 31
	v_cmp_gt_u32_e32 vcc, 2, v241
	v_mov_b32_dpp v155, v225 row_ror:1 row_mask:0xf bank_mask:0xf
	v_mov_b32_dpp v154, v225 row_ror:2 row_mask:0xf bank_mask:0xf
	v_mov_b32_dpp v157, v229 row_ror:1 row_mask:0xf bank_mask:0xf
	v_mov_b32_dpp v156, v229 row_ror:2 row_mask:0xf bank_mask:0xf
	v_mov_b32_dpp v159, v231 row_ror:1 row_mask:0xf bank_mask:0xf
	v_mov_b32_dpp v158, v231 row_ror:2 row_mask:0xf bank_mask:0xf
	v_mov_b32_dpp v208, v234 row_ror:1 row_mask:0xf bank_mask:0xf
	v_mov_b32_dpp v207, v234 row_ror:2 row_mask:0xf bank_mask:0xf
	v_mov_b32_dpp v211, v235 row_ror:1 row_mask:0xf bank_mask:0xf
	v_mov_b32_dpp v210, v235 row_ror:2 row_mask:0xf bank_mask:0xf
	v_mov_b32_dpp v214, v153 row_ror:1 row_mask:0xf bank_mask:0xf
	v_mov_b32_dpp v213, v153 row_ror:2 row_mask:0xf bank_mask:0xf
	v_mov_b32_dpp v218, v239 row_ror:1 row_mask:0xf bank_mask:0xf
	v_mov_b32_dpp v217, v239 row_ror:2 row_mask:0xf bank_mask:0xf
	v_mov_b32_dpp v221, v240 row_ror:1 row_mask:0xf bank_mask:0xf
	v_mov_b32_dpp v220, v240 row_ror:2 row_mask:0xf bank_mask:0xf
	s_and_b64 s[12:13], s[12:13], s[14:15]
	v_lshlrev_b32_e32 v168, 1, v168
	v_lshlrev_b32_e32 v152, 1, v170
	s_and_saveexec_b64 s[62:63], s[12:13]
	s_cbranch_execz .LBB0_663
	s_waitcnt lgkmcnt(0)
	v_cndmask_b32_e64 v242, v221, v237, s[6:7]
	v_cndmask_b32_e64 v237, v237, v238, s[6:7]
	s_cmp_eq_u64 vcc, 0
	v_cndmask_b32_e64 v237, v220, v237, s[4:5]
	v_cmp_eq_u32_e64 s[14:15], 0, v241
	s_cselect_b64 s[12:13], -1, 0
	v_cndmask_b32_e64 v237, v237, 0, vcc
	v_cndmask_b32_e64 v242, v242, 0, s[14:15]
	v_fma_f32 v241, v79, v237, v75
	v_fmac_f32_e32 v241, v83, v242
	v_fmac_f32_e32 v241, v87, v240
	v_mul_f32_e32 v237, 0xbfb8aa3b, v241
	v_exp_f32_e32 v237, v237
	v_mov_b32_e32 v240, v151
	v_cndmask_b32_e64 v151, v218, v236, s[6:7]
	v_cndmask_b32_e64 v238, v236, v183, s[6:7]
	v_cndmask_b32_e64 v236, v151, 0, s[14:15]
	v_cndmask_b32_e64 v151, v217, v238, s[4:5]
	v_add_f32_e32 v183, 1.0, v237
	v_cndmask_b32_e64 v151, v151, 0, vcc
	v_fma_f32 v151, v78, v151, v74
	v_fmac_f32_e32 v151, v82, v236
	v_fmac_f32_e32 v151, v86, v239
	v_mul_f32_e32 v236, 0xbfb8aa3b, v151
	v_rcp_f32_e32 v183, v183
	v_exp_f32_e32 v238, v236
	v_cndmask_b32_e64 v233, v232, v233, s[6:7]
	v_cndmask_b32_e64 v232, v214, v232, s[6:7]
	v_pk_mul_f32 v[236:237], v[240:241], v[182:183]
	v_add_f32_e32 v183, 1.0, v238
	v_cndmask_b32_e64 v233, v213, v233, s[4:5]
	v_cndmask_b32_e64 v232, v232, 0, s[14:15]
	v_cndmask_b32_e64 v233, v233, 0, vcc
	v_fma_f32 v233, v77, v233, v73
	v_fmac_f32_e32 v233, v81, v232
	v_fmac_f32_e32 v233, v85, v153
	v_mul_f32_e32 v153, 0xbfb8aa3b, v233
	v_exp_f32_e32 v153, v153
	v_rcp_f32_e32 v183, v183
	v_mov_b32_e32 v232, v149
	v_cndmask_b32_e64 v149, v211, v228, s[6:7]
	v_add_f32_e32 v153, 1.0, v153
	v_cndmask_b32_e64 v230, v228, v230, s[6:7]
	v_pk_mul_f32 v[150:151], v[150:151], v[182:183]
	v_rcp_f32_e32 v183, v153
	v_cndmask_b32_e64 v153, v149, 0, s[14:15]
	v_cndmask_b32_e64 v149, v210, v230, s[4:5]
	v_cndmask_b32_e64 v149, v149, 0, vcc
	v_fma_f32 v149, v76, v149, v72
	v_fmac_f32_e32 v149, v80, v153
	v_fmac_f32_e32 v149, v84, v235
	v_mul_f32_e32 v153, 0xbfb8aa3b, v149
	v_exp_f32_e32 v153, v153
	v_pk_mul_f32 v[232:233], v[232:233], v[182:183]
	v_cndmask_b32_e64 v224, v223, v224, s[6:7]
	v_cndmask_b32_e64 v216, v215, v216, s[6:7]
	v_add_f32_e32 v153, 1.0, v153
	v_rcp_f32_e32 v183, v153
	v_cndmask_b32_e64 v153, v208, v223, s[6:7]
	v_cndmask_b32_e64 v153, v153, 0, s[14:15]
	v_cndmask_b32_e64 v223, v207, v224, s[4:5]
	v_cndmask_b32_e64 v223, v223, 0, vcc
	v_fma_f32 v223, v59, v223, v55
	v_fmac_f32_e32 v223, v63, v153
	v_fmac_f32_e32 v223, v67, v234
	v_mul_f32_e32 v153, 0xbfb8aa3b, v223
	v_exp_f32_e32 v153, v153
	v_cndmask_b32_e64 v224, v219, v222, s[6:7]
	v_mov_b32_e32 v222, v147
	v_cndmask_b32_e64 v147, v159, v219, s[6:7]
	v_add_f32_e32 v153, 1.0, v153
	v_pk_mul_f32 v[148:149], v[148:149], v[182:183]
	v_rcp_f32_e32 v183, v153
	v_cndmask_b32_e64 v153, v147, 0, s[14:15]
	v_cndmask_b32_e64 v147, v158, v224, s[4:5]
	v_cndmask_b32_e64 v147, v147, 0, vcc
	v_fma_f32 v147, v58, v147, v54
	v_fmac_f32_e32 v147, v62, v153
	v_fmac_f32_e32 v147, v66, v231
	v_mul_f32_e32 v153, 0xbfb8aa3b, v147
	v_exp_f32_e32 v153, v153
	v_pk_mul_f32 v[222:223], v[222:223], v[182:183]
	v_mul_f32_e32 v150, v150, v151
	v_mov_b32_e32 v230, v145
	v_add_f32_e32 v153, 1.0, v153
	v_rcp_f32_e32 v183, v153
	v_cndmask_b32_e64 v153, v157, v215, s[6:7]
	v_cndmask_b32_e64 v153, v153, 0, s[14:15]
	v_cndmask_b32_e64 v215, v156, v216, s[4:5]
	v_cndmask_b32_e64 v215, v215, 0, vcc
	v_fma_f32 v231, v57, v215, v53
	v_fmac_f32_e32 v231, v61, v153
	v_fmac_f32_e32 v231, v65, v229
	v_mul_f32_e32 v153, 0xbfb8aa3b, v231
	v_exp_f32_e32 v153, v153
	v_cndmask_b32_e64 v145, v155, v209, s[6:7]
	v_cndmask_b32_e64 v212, v209, v212, s[6:7]
	v_pk_mul_f32 v[146:147], v[146:147], v[182:183]
	v_add_f32_e32 v151, 1.0, v153
	v_rcp_f32_e32 v183, v151
	v_cndmask_b32_e64 v151, v145, 0, s[14:15]
	v_cndmask_b32_e64 v145, v154, v212, s[4:5]
	v_cndmask_b32_e64 v145, v145, 0, vcc
	v_fma_f32 v145, v56, v145, v52
	v_fmac_f32_e32 v145, v60, v151
	v_fmac_f32_e32 v145, v64, v225
	v_mul_f32_e32 v151, 0xbfb8aa3b, v145
	v_exp_f32_e32 v151, v151
	v_mul_f32_e32 v209, v148, v149
	v_pk_mul_f32 v[148:149], v[230:231], v[182:183]
	v_mul_f32_e32 v146, v146, v147
	v_add_f32_e32 v151, 1.0, v151
	v_rcp_f32_e32 v183, v151
	v_mul_f32_e32 v147, v148, v149
	v_mul_f32_e32 v215, v236, v237
	v_mul_f32_e32 v153, v232, v233
	v_pk_mul_f32 v[144:145], v[144:145], v[182:183]
	v_mul_f32_e32 v151, v222, v223
	v_mul_f32_e32 v144, v144, v145
	v_cvt_pk_bf16_f32 v144, v144, v147
	v_cvt_pk_bf16_f32 v145, v146, v151
	v_cvt_pk_bf16_f32 v146, v209, v153
	v_cvt_pk_bf16_f32 v147, v150, v215
	v_ashrrev_i32_e32 v150, 4, v181
	v_mov_b64_e32 v[148:149], s[60:61]
	v_mad_i64_i32 v[148:149], s[12:13], v150, s82, v[148:149]
	v_lshlrev_b64 v[148:149], 10, v[148:149]
	v_lshl_add_u64 v[148:149], s[36:37], 0, v[148:149]
	v_lshl_add_u64 v[148:149], v[148:149], 0, v[168:169]
	v_mov_b32_e32 v153, v169
	v_lshl_add_u64 v[148:149], v[148:149], 0, v[152:153]
	global_store_dwordx4 v[148:149], v[144:147], off
.LBB0_663:
	s_or_b64 exec, exec, s[62:63]
	s_nop 0
	v_fmamk_f32 v144, v206, 0x39800000, v191
	v_rsq_f32_e32 v144, v144
	s_waitcnt lgkmcnt(0)
	v_and_b32_e32 v222, 0xfff, v204
	v_mul_f32_e32 v153, v140, v144
	v_mul_f32_e32 v206, v141, v144
	v_mul_f32_e32 v209, v142, v144
	v_mul_f32_e32 v212, v143, v144
	v_mul_f32_e32 v215, v136, v144
	v_mul_f32_e32 v216, v137, v144
	v_mul_f32_e32 v219, v138, v144
	v_mul_f32_e32 v145, v139, v144
	v_cmp_le_i32_e64 s[12:13], s53, v204
	v_cmp_gt_i32_e64 s[14:15], s83, v181
	v_cmp_gt_u32_e32 vcc, 2, v222
	v_mov_b32_dpp v137, v153 row_ror:1 row_mask:0xf bank_mask:0xf
	v_mov_b32_dpp v136, v153 row_ror:2 row_mask:0xf bank_mask:0xf
	v_mov_b32_dpp v139, v206 row_ror:1 row_mask:0xf bank_mask:0xf
	v_mov_b32_dpp v138, v206 row_ror:2 row_mask:0xf bank_mask:0xf
	v_mov_b32_dpp v141, v209 row_ror:1 row_mask:0xf bank_mask:0xf
	v_mov_b32_dpp v140, v209 row_ror:2 row_mask:0xf bank_mask:0xf
	v_mov_b32_dpp v143, v212 row_ror:1 row_mask:0xf bank_mask:0xf
	v_mov_b32_dpp v142, v212 row_ror:2 row_mask:0xf bank_mask:0xf
	v_mov_b32_dpp v147, v215 row_ror:1 row_mask:0xf bank_mask:0xf
	v_mov_b32_dpp v146, v215 row_ror:2 row_mask:0xf bank_mask:0xf
	v_mov_b32_dpp v149, v216 row_ror:1 row_mask:0xf bank_mask:0xf
	v_mov_b32_dpp v148, v216 row_ror:2 row_mask:0xf bank_mask:0xf
	v_mov_b32_dpp v151, v219 row_ror:1 row_mask:0xf bank_mask:0xf
	v_mov_b32_dpp v150, v219 row_ror:2 row_mask:0xf bank_mask:0xf
	v_mov_b32_dpp v183, v145 row_ror:1 row_mask:0xf bank_mask:0xf
	v_mov_b32_dpp v182, v145 row_ror:2 row_mask:0xf bank_mask:0xf
	s_and_b64 s[12:13], s[14:15], s[12:13]
	s_and_saveexec_b64 s[62:63], s[12:13]
	s_cbranch_execz .LBB0_665
	s_cmp_eq_u64 vcc, 0
	v_cndmask_b32_e64 v221, v183, v221, s[6:7]
	v_cmp_eq_u32_e64 s[14:15], 0, v222
	s_cselect_b64 s[12:13], -1, 0
	v_cndmask_b32_e64 v220, v182, v220, s[4:5]
	v_cndmask_b32_e64 v222, v221, 0, s[14:15]
	v_cndmask_b32_e64 v220, v220, 0, vcc
	v_fma_f32 v221, v79, v220, v75
	v_mov_b32_e32 v220, v135
	v_cndmask_b32_e64 v135, v151, v218, s[6:7]
	v_fmac_f32_e32 v221, v83, v222
	v_cndmask_b32_e64 v218, v135, 0, s[14:15]
	v_fmac_f32_e32 v221, v87, v145
	v_cndmask_b32_e64 v135, v150, v217, s[4:5]
	v_mul_f32_e32 v145, 0xbfb8aa3b, v221
	v_exp_f32_e32 v145, v145
	v_cndmask_b32_e64 v135, v135, 0, vcc
	v_fma_f32 v135, v78, v135, v74
	v_fmac_f32_e32 v135, v82, v218
	v_fmac_f32_e32 v135, v86, v219
	v_add_f32_e32 v145, 1.0, v145
	v_mul_f32_e32 v217, 0xbfb8aa3b, v135
	v_rcp_f32_e32 v145, v145
	v_exp_f32_e32 v217, v217
	v_cndmask_b32_e64 v214, v149, v214, s[6:7]
	v_cndmask_b32_e64 v213, v148, v213, s[4:5]
	v_pk_mul_f32 v[218:219], v[220:221], v[144:145]
	v_add_f32_e32 v145, 1.0, v217
	v_cndmask_b32_e64 v214, v214, 0, s[14:15]
	v_cndmask_b32_e64 v213, v213, 0, vcc
	v_fma_f32 v217, v77, v213, v73
	v_fmac_f32_e32 v217, v81, v214
	v_fmac_f32_e32 v217, v85, v216
	v_mov_b32_e32 v216, v133
	v_cndmask_b32_e64 v133, v147, v211, s[6:7]
	v_cndmask_b32_e64 v211, v133, 0, s[14:15]
	v_cndmask_b32_e64 v133, v146, v210, s[4:5]
	v_mul_f32_e32 v213, 0xbfb8aa3b, v217
	v_rcp_f32_e32 v145, v145
	v_exp_f32_e32 v213, v213
	v_cndmask_b32_e64 v133, v133, 0, vcc
	v_fma_f32 v133, v76, v133, v72
	v_fmac_f32_e32 v133, v80, v211
	v_fmac_f32_e32 v133, v84, v215
	v_pk_mul_f32 v[134:135], v[134:135], v[144:145]
	v_add_f32_e32 v145, 1.0, v213
	v_mul_f32_e32 v210, 0xbfb8aa3b, v133
	v_rcp_f32_e32 v145, v145
	v_exp_f32_e32 v213, v210
	v_cndmask_b32_e64 v208, v143, v208, s[6:7]
	v_cndmask_b32_e64 v207, v142, v207, s[4:5]
	v_pk_mul_f32 v[210:211], v[216:217], v[144:145]
	v_add_f32_e32 v145, 1.0, v213
	v_cndmask_b32_e64 v208, v208, 0, s[14:15]
	v_cndmask_b32_e64 v207, v207, 0, vcc
	v_fma_f32 v213, v59, v207, v55
	v_fmac_f32_e32 v213, v63, v208
	v_fmac_f32_e32 v213, v67, v212
	v_mov_b32_e32 v212, v131
	v_cndmask_b32_e64 v131, v141, v159, s[6:7]
	v_cndmask_b32_e64 v159, v131, 0, s[14:15]
	v_cndmask_b32_e64 v131, v140, v158, s[4:5]
	v_mul_f32_e32 v207, 0xbfb8aa3b, v213
	v_rcp_f32_e32 v145, v145
	v_exp_f32_e32 v207, v207
	v_cndmask_b32_e64 v131, v131, 0, vcc
	v_fma_f32 v131, v58, v131, v54
	v_fmac_f32_e32 v131, v62, v159
	v_fmac_f32_e32 v131, v66, v209
	v_pk_mul_f32 v[132:133], v[132:133], v[144:145]
	v_add_f32_e32 v145, 1.0, v207
	v_mul_f32_e32 v158, 0xbfb8aa3b, v131
	v_rcp_f32_e32 v145, v145
	v_exp_f32_e32 v207, v158
	v_cndmask_b32_e64 v157, v139, v157, s[6:7]
	v_cndmask_b32_e64 v156, v138, v156, s[4:5]
	v_pk_mul_f32 v[158:159], v[212:213], v[144:145]
	v_add_f32_e32 v145, 1.0, v207
	v_cndmask_b32_e64 v207, v157, 0, s[14:15]
	v_cndmask_b32_e64 v156, v156, 0, vcc
	v_fma_f32 v157, v57, v156, v53
	v_fmac_f32_e32 v157, v61, v207
	v_fmac_f32_e32 v157, v65, v206
	v_mul_f32_e32 v156, 0xbfb8aa3b, v157
	v_exp_f32_e32 v156, v156
	v_rcp_f32_e32 v145, v145
	v_mul_f32_e32 v134, v134, v135
	v_mul_f32_e32 v206, v218, v219
	v_add_f32_e32 v135, 1.0, v156
	v_mov_b32_e32 v156, v129
	v_cndmask_b32_e64 v129, v137, v155, s[6:7]
	v_pk_mul_f32 v[130:131], v[130:131], v[144:145]
	v_rcp_f32_e32 v145, v135
	v_cndmask_b32_e64 v135, v129, 0, s[14:15]
	v_cndmask_b32_e64 v129, v136, v154, s[4:5]
	v_cndmask_b32_e64 v129, v129, 0, vcc
	v_fma_f32 v129, v56, v129, v52
	v_fmac_f32_e32 v129, v60, v135
	v_fmac_f32_e32 v129, v64, v153
	v_mul_f32_e32 v135, 0xbfb8aa3b, v129
	v_exp_f32_e32 v135, v135
	v_mul_f32_e32 v154, v132, v133
	v_pk_mul_f32 v[132:133], v[156:157], v[144:145]
	v_mul_f32_e32 v130, v130, v131
	v_add_f32_e32 v135, 1.0, v135
	v_rcp_f32_e32 v145, v135
	v_mul_f32_e32 v131, v132, v133
	v_mul_f32_e32 v153, v210, v211
	v_mul_f32_e32 v135, v158, v159
	v_pk_mul_f32 v[128:129], v[128:129], v[144:145]
	v_mov_b64_e32 v[132:133], s[60:61]
	v_mul_f32_e32 v128, v128, v129
	v_cvt_pk_bf16_f32 v128, v128, v131
	v_cvt_pk_bf16_f32 v129, v130, v135
	v_cvt_pk_bf16_f32 v130, v154, v153
	v_cvt_pk_bf16_f32 v131, v134, v206
	v_ashrrev_i32_e32 v134, 4, v204
	v_mad_i64_i32 v[132:133], s[12:13], v134, s82, v[132:133]
	v_lshlrev_b64 v[132:133], 10, v[132:133]
	v_lshl_add_u64 v[132:133], s[36:37], 0, v[132:133]
	v_lshl_add_u64 v[132:133], v[132:133], 0, v[168:169]
	v_mov_b32_e32 v153, v169
	v_lshl_add_u64 v[132:133], v[132:133], 0, v[152:153]
	global_store_dwordx4 v[132:133], v[128:131], off
.LBB0_665:
	s_or_b64 exec, exec, s[62:63]
	s_nop 0
	v_fmamk_f32 v128, v205, 0x39800000, v191
	v_rsq_f32_e32 v128, v128
	v_and_b32_e32 v204, 0xfff, v202
	v_mul_f32_e32 v153, v124, v128
	v_mul_f32_e32 v154, v125, v128
	v_mul_f32_e32 v155, v126, v128
	v_mul_f32_e32 v156, v127, v128
	v_mul_f32_e32 v157, v120, v128
	v_mul_f32_e32 v158, v121, v128
	v_mul_f32_e32 v159, v122, v128
	v_mul_f32_e32 v129, v123, v128
	v_cmp_le_i32_e64 s[12:13], s53, v202
	v_cmp_gt_i32_e64 s[14:15], s84, v181
	v_cmp_gt_u32_e32 vcc, 2, v204
	v_mov_b32_dpp v121, v153 row_ror:1 row_mask:0xf bank_mask:0xf
	v_mov_b32_dpp v120, v153 row_ror:2 row_mask:0xf bank_mask:0xf
	v_mov_b32_dpp v123, v154 row_ror:1 row_mask:0xf bank_mask:0xf
	v_mov_b32_dpp v122, v154 row_ror:2 row_mask:0xf bank_mask:0xf
	v_mov_b32_dpp v125, v155 row_ror:1 row_mask:0xf bank_mask:0xf
	v_mov_b32_dpp v124, v155 row_ror:2 row_mask:0xf bank_mask:0xf
	v_mov_b32_dpp v127, v156 row_ror:1 row_mask:0xf bank_mask:0xf
	v_mov_b32_dpp v126, v156 row_ror:2 row_mask:0xf bank_mask:0xf
	v_mov_b32_dpp v131, v157 row_ror:1 row_mask:0xf bank_mask:0xf
	v_mov_b32_dpp v130, v157 row_ror:2 row_mask:0xf bank_mask:0xf
	v_mov_b32_dpp v133, v158 row_ror:1 row_mask:0xf bank_mask:0xf
	v_mov_b32_dpp v132, v158 row_ror:2 row_mask:0xf bank_mask:0xf
	v_mov_b32_dpp v135, v159 row_ror:1 row_mask:0xf bank_mask:0xf
	v_mov_b32_dpp v134, v159 row_ror:2 row_mask:0xf bank_mask:0xf
	v_mov_b32_dpp v145, v129 row_ror:1 row_mask:0xf bank_mask:0xf
	v_mov_b32_dpp v144, v129 row_ror:2 row_mask:0xf bank_mask:0xf
	s_and_b64 s[12:13], s[14:15], s[12:13]
	s_and_saveexec_b64 s[62:63], s[12:13]
	s_cbranch_execz .LBB0_667
	s_cmp_eq_u64 vcc, 0
	v_cndmask_b32_e64 v183, v145, v183, s[6:7]
	v_cmp_eq_u32_e64 s[14:15], 0, v204
	s_cselect_b64 s[12:13], -1, 0
	v_cndmask_b32_e64 v182, v144, v182, s[4:5]
	v_cndmask_b32_e64 v204, v183, 0, s[14:15]
	v_cndmask_b32_e64 v182, v182, 0, vcc
	v_fma_f32 v183, v79, v182, v75
	v_mov_b32_e32 v182, v119
	v_cndmask_b32_e64 v119, v135, v151, s[6:7]
	v_fmac_f32_e32 v183, v83, v204
	v_cndmask_b32_e64 v151, v119, 0, s[14:15]
	v_fmac_f32_e32 v183, v87, v129
	v_cndmask_b32_e64 v119, v134, v150, s[4:5]
	v_mul_f32_e32 v129, 0xbfb8aa3b, v183
	v_exp_f32_e32 v129, v129
	v_cndmask_b32_e64 v119, v119, 0, vcc
	v_fma_f32 v119, v78, v119, v74
	v_fmac_f32_e32 v119, v82, v151
	v_fmac_f32_e32 v119, v86, v159
	v_add_f32_e32 v129, 1.0, v129
	v_mul_f32_e32 v150, 0xbfb8aa3b, v119
	v_rcp_f32_e32 v129, v129
	v_exp_f32_e32 v159, v150
	v_cndmask_b32_e64 v149, v133, v149, s[6:7]
	v_cndmask_b32_e64 v148, v132, v148, s[4:5]
	v_pk_mul_f32 v[150:151], v[182:183], v[128:129]
	v_add_f32_e32 v129, 1.0, v159
	v_cndmask_b32_e64 v159, v149, 0, s[14:15]
	v_cndmask_b32_e64 v148, v148, 0, vcc
	v_fma_f32 v149, v77, v148, v73
	v_fmac_f32_e32 v149, v81, v159
	v_fmac_f32_e32 v149, v85, v158
	v_mul_f32_e32 v148, 0xbfb8aa3b, v149
	v_rcp_f32_e32 v129, v129
	v_exp_f32_e32 v148, v148
	v_cndmask_b32_e64 v143, v127, v143, s[6:7]
	v_cndmask_b32_e64 v142, v126, v142, s[4:5]
	v_pk_mul_f32 v[118:119], v[118:119], v[128:129]
	v_add_f32_e32 v129, 1.0, v148
	v_mov_b32_e32 v148, v117
	v_cndmask_b32_e64 v117, v131, v147, s[6:7]
	v_cndmask_b32_e64 v147, v117, 0, s[14:15]
	v_cndmask_b32_e64 v117, v130, v146, s[4:5]
	v_cndmask_b32_e64 v117, v117, 0, vcc
	v_rcp_f32_e32 v129, v129
	v_fma_f32 v117, v76, v117, v72
	v_fmac_f32_e32 v117, v80, v147
	v_fmac_f32_e32 v117, v84, v157
	v_mul_f32_e32 v146, 0xbfb8aa3b, v117
	v_exp_f32_e32 v157, v146
	v_pk_mul_f32 v[146:147], v[148:149], v[128:129]
	v_cndmask_b32_e64 v148, v143, 0, s[14:15]
	v_cndmask_b32_e64 v142, v142, 0, vcc
	v_fma_f32 v143, v59, v142, v55
	v_fmac_f32_e32 v143, v63, v148
	v_fmac_f32_e32 v143, v67, v156
	v_add_f32_e32 v129, 1.0, v157
	v_mul_f32_e32 v142, 0xbfb8aa3b, v143
	v_rcp_f32_e32 v129, v129
	v_exp_f32_e32 v142, v142
	v_cndmask_b32_e64 v139, v123, v139, s[6:7]
	v_cndmask_b32_e64 v138, v122, v138, s[4:5]
	v_pk_mul_f32 v[116:117], v[116:117], v[128:129]
	v_add_f32_e32 v129, 1.0, v142
	v_mov_b32_e32 v142, v115
	v_cndmask_b32_e64 v115, v125, v141, s[6:7]
	v_cndmask_b32_e64 v141, v115, 0, s[14:15]
	v_cndmask_b32_e64 v115, v124, v140, s[4:5]
	v_cndmask_b32_e64 v115, v115, 0, vcc
	v_rcp_f32_e32 v129, v129
	v_fma_f32 v115, v58, v115, v54
	v_fmac_f32_e32 v115, v62, v141
	v_fmac_f32_e32 v115, v66, v155
	v_mul_f32_e32 v140, 0xbfb8aa3b, v115
	v_exp_f32_e32 v148, v140
	v_pk_mul_f32 v[140:141], v[142:143], v[128:129]
	v_cndmask_b32_e64 v142, v139, 0, s[14:15]
	v_cndmask_b32_e64 v138, v138, 0, vcc
	v_fma_f32 v139, v57, v138, v53
	v_fmac_f32_e32 v139, v61, v142
	v_fmac_f32_e32 v139, v65, v154
	v_mul_f32_e32 v138, 0xbfb8aa3b, v139
	v_add_f32_e32 v129, 1.0, v148
	v_exp_f32_e32 v138, v138
	v_rcp_f32_e32 v129, v129
	v_mul_f32_e32 v118, v118, v119
	v_mul_f32_e32 v142, v150, v151
	v_add_f32_e32 v119, 1.0, v138
	v_mov_b32_e32 v138, v113
	v_cndmask_b32_e64 v113, v121, v137, s[6:7]
	v_pk_mul_f32 v[114:115], v[114:115], v[128:129]
	v_rcp_f32_e32 v129, v119
	v_cndmask_b32_e64 v119, v113, 0, s[14:15]
	v_cndmask_b32_e64 v113, v120, v136, s[4:5]
	v_cndmask_b32_e64 v113, v113, 0, vcc
	v_fma_f32 v113, v56, v113, v52
	v_fmac_f32_e32 v113, v60, v119
	v_fmac_f32_e32 v113, v64, v153
	v_mul_f32_e32 v119, 0xbfb8aa3b, v113
	v_exp_f32_e32 v119, v119
	v_mul_f32_e32 v137, v116, v117
	v_pk_mul_f32 v[116:117], v[138:139], v[128:129]
	v_mul_f32_e32 v114, v114, v115
	v_add_f32_e32 v119, 1.0, v119
	v_rcp_f32_e32 v129, v119
	v_mul_f32_e32 v115, v116, v117
	v_mul_f32_e32 v136, v146, v147
	v_mul_f32_e32 v119, v140, v141
	v_pk_mul_f32 v[112:113], v[112:113], v[128:129]
	v_mov_b64_e32 v[116:117], s[60:61]
	v_mul_f32_e32 v112, v112, v113
	v_cvt_pk_bf16_f32 v112, v112, v115
	v_cvt_pk_bf16_f32 v113, v114, v119
	v_cvt_pk_bf16_f32 v114, v137, v136
	v_cvt_pk_bf16_f32 v115, v118, v142
	v_ashrrev_i32_e32 v118, 4, v202
	v_mad_i64_i32 v[116:117], s[12:13], v118, s82, v[116:117]
	v_lshlrev_b64 v[116:117], 10, v[116:117]
	v_lshl_add_u64 v[116:117], s[36:37], 0, v[116:117]
	v_lshl_add_u64 v[116:117], v[116:117], 0, v[168:169]
	v_mov_b32_e32 v153, v169
	v_lshl_add_u64 v[116:117], v[116:117], 0, v[152:153]
	global_store_dwordx4 v[116:117], v[112:115], off
.LBB0_667:
	s_or_b64 exec, exec, s[62:63]
	s_nop 0
	v_fmamk_f32 v112, v203, 0x39800000, v191
	v_rsq_f32_e32 v112, v112
	v_and_b32_e32 v143, 0xfff, v200
	v_mul_f32_e32 v136, v108, v112
	v_mul_f32_e32 v137, v109, v112
	v_mul_f32_e32 v138, v110, v112
	v_mul_f32_e32 v139, v111, v112
	v_mul_f32_e32 v140, v104, v112
	v_mul_f32_e32 v141, v105, v112
	v_mul_f32_e32 v142, v106, v112
	v_mul_f32_e32 v113, v107, v112
	v_cmp_le_i32_e64 s[12:13], s53, v200
	v_cmp_gt_i32_e64 s[14:15], s85, v181
	v_cmp_gt_u32_e32 vcc, 2, v143
	v_mov_b32_dpp v105, v136 row_ror:1 row_mask:0xf bank_mask:0xf
	v_mov_b32_dpp v104, v136 row_ror:2 row_mask:0xf bank_mask:0xf
	v_mov_b32_dpp v107, v137 row_ror:1 row_mask:0xf bank_mask:0xf
	v_mov_b32_dpp v106, v137 row_ror:2 row_mask:0xf bank_mask:0xf
	v_mov_b32_dpp v109, v138 row_ror:1 row_mask:0xf bank_mask:0xf
	v_mov_b32_dpp v108, v138 row_ror:2 row_mask:0xf bank_mask:0xf
	v_mov_b32_dpp v111, v139 row_ror:1 row_mask:0xf bank_mask:0xf
	v_mov_b32_dpp v110, v139 row_ror:2 row_mask:0xf bank_mask:0xf
	v_mov_b32_dpp v115, v140 row_ror:1 row_mask:0xf bank_mask:0xf
	v_mov_b32_dpp v114, v140 row_ror:2 row_mask:0xf bank_mask:0xf
	v_mov_b32_dpp v117, v141 row_ror:1 row_mask:0xf bank_mask:0xf
	v_mov_b32_dpp v116, v141 row_ror:2 row_mask:0xf bank_mask:0xf
	v_mov_b32_dpp v119, v142 row_ror:1 row_mask:0xf bank_mask:0xf
	v_mov_b32_dpp v118, v142 row_ror:2 row_mask:0xf bank_mask:0xf
	v_mov_b32_dpp v129, v113 row_ror:1 row_mask:0xf bank_mask:0xf
	v_mov_b32_dpp v128, v113 row_ror:2 row_mask:0xf bank_mask:0xf
	s_and_b64 s[12:13], s[14:15], s[12:13]
	s_and_saveexec_b64 s[62:63], s[12:13]
	s_cbranch_execz .LBB0_669
	s_cmp_eq_u64 vcc, 0
	v_cndmask_b32_e64 v145, v129, v145, s[6:7]
	v_cmp_eq_u32_e64 s[14:15], 0, v143
	s_cselect_b64 s[12:13], -1, 0
	v_cndmask_b32_e64 v144, v128, v144, s[4:5]
	v_cndmask_b32_e64 v143, v145, 0, s[14:15]
	v_cndmask_b32_e64 v144, v144, 0, vcc
	v_fma_f32 v145, v79, v144, v75
	v_mov_b32_e32 v144, v103
	v_cndmask_b32_e64 v103, v119, v135, s[6:7]
	v_fmac_f32_e32 v145, v83, v143
	v_cndmask_b32_e64 v135, v103, 0, s[14:15]
	v_fmac_f32_e32 v145, v87, v113
	v_cndmask_b32_e64 v103, v118, v134, s[4:5]
	v_mul_f32_e32 v113, 0xbfb8aa3b, v145
	v_exp_f32_e32 v113, v113
	v_cndmask_b32_e64 v103, v103, 0, vcc
	v_fma_f32 v103, v78, v103, v74
	v_fmac_f32_e32 v103, v82, v135
	v_fmac_f32_e32 v103, v86, v142
	v_add_f32_e32 v113, 1.0, v113
	v_mul_f32_e32 v134, 0xbfb8aa3b, v103
	v_rcp_f32_e32 v113, v113
	v_exp_f32_e32 v142, v134
	v_cndmask_b32_e64 v133, v117, v133, s[6:7]
	v_cndmask_b32_e64 v132, v116, v132, s[4:5]
	v_pk_mul_f32 v[134:135], v[144:145], v[112:113]
	v_add_f32_e32 v113, 1.0, v142
	v_cndmask_b32_e64 v142, v133, 0, s[14:15]
	v_cndmask_b32_e64 v132, v132, 0, vcc
	v_fma_f32 v133, v77, v132, v73
	v_fmac_f32_e32 v133, v81, v142
	v_fmac_f32_e32 v133, v85, v141
	v_mul_f32_e32 v132, 0xbfb8aa3b, v133
	v_rcp_f32_e32 v113, v113
	v_exp_f32_e32 v132, v132
	v_cndmask_b32_e64 v127, v111, v127, s[6:7]
	v_cndmask_b32_e64 v126, v110, v126, s[4:5]
	v_pk_mul_f32 v[102:103], v[102:103], v[112:113]
	v_add_f32_e32 v113, 1.0, v132
	v_mov_b32_e32 v132, v101
	v_cndmask_b32_e64 v101, v115, v131, s[6:7]
	v_cndmask_b32_e64 v131, v101, 0, s[14:15]
	v_cndmask_b32_e64 v101, v114, v130, s[4:5]
	v_cndmask_b32_e64 v101, v101, 0, vcc
	v_rcp_f32_e32 v113, v113
	v_fma_f32 v101, v76, v101, v72
	v_fmac_f32_e32 v101, v80, v131
	v_fmac_f32_e32 v101, v84, v140
	v_mul_f32_e32 v130, 0xbfb8aa3b, v101
	v_exp_f32_e32 v140, v130
	v_pk_mul_f32 v[130:131], v[132:133], v[112:113]
	v_cndmask_b32_e64 v132, v127, 0, s[14:15]
	v_cndmask_b32_e64 v126, v126, 0, vcc
	v_fma_f32 v127, v59, v126, v55
	v_fmac_f32_e32 v127, v63, v132
	v_fmac_f32_e32 v127, v67, v139
	v_add_f32_e32 v113, 1.0, v140
	v_mul_f32_e32 v126, 0xbfb8aa3b, v127
	v_rcp_f32_e32 v113, v113
	v_exp_f32_e32 v126, v126
	v_cndmask_b32_e64 v123, v107, v123, s[6:7]
	v_cndmask_b32_e64 v122, v106, v122, s[4:5]
	v_pk_mul_f32 v[100:101], v[100:101], v[112:113]
	v_add_f32_e32 v113, 1.0, v126
	v_mov_b32_e32 v126, v99
	v_cndmask_b32_e64 v99, v109, v125, s[6:7]
	v_cndmask_b32_e64 v125, v99, 0, s[14:15]
	v_cndmask_b32_e64 v99, v108, v124, s[4:5]
	v_cndmask_b32_e64 v99, v99, 0, vcc
	v_rcp_f32_e32 v113, v113
	v_fma_f32 v99, v58, v99, v54
	v_fmac_f32_e32 v99, v62, v125
	v_fmac_f32_e32 v99, v66, v138
	v_mul_f32_e32 v124, 0xbfb8aa3b, v99
	v_exp_f32_e32 v132, v124
	v_pk_mul_f32 v[124:125], v[126:127], v[112:113]
	v_cndmask_b32_e64 v126, v123, 0, s[14:15]
	v_cndmask_b32_e64 v122, v122, 0, vcc
	v_fma_f32 v123, v57, v122, v53
	v_fmac_f32_e32 v123, v61, v126
	v_fmac_f32_e32 v123, v65, v137
	v_mul_f32_e32 v122, 0xbfb8aa3b, v123
	v_add_f32_e32 v113, 1.0, v132
	v_exp_f32_e32 v122, v122
	v_rcp_f32_e32 v113, v113
	v_mul_f32_e32 v102, v102, v103
	v_mul_f32_e32 v126, v134, v135
	v_add_f32_e32 v103, 1.0, v122
	v_mov_b32_e32 v122, v97
	v_cndmask_b32_e64 v97, v105, v121, s[6:7]
	v_pk_mul_f32 v[98:99], v[98:99], v[112:113]
	v_rcp_f32_e32 v113, v103
	v_cndmask_b32_e64 v103, v97, 0, s[14:15]
	v_cndmask_b32_e64 v97, v104, v120, s[4:5]
	v_cndmask_b32_e64 v97, v97, 0, vcc
	v_fma_f32 v97, v56, v97, v52
	v_fmac_f32_e32 v97, v60, v103
	v_fmac_f32_e32 v97, v64, v136
	v_mul_f32_e32 v103, 0xbfb8aa3b, v97
	v_exp_f32_e32 v103, v103
	v_mul_f32_e32 v121, v100, v101
	v_pk_mul_f32 v[100:101], v[122:123], v[112:113]
	v_mul_f32_e32 v98, v98, v99
	v_add_f32_e32 v103, 1.0, v103
	v_rcp_f32_e32 v113, v103
	v_mul_f32_e32 v99, v100, v101
	v_mul_f32_e32 v120, v130, v131
	v_mul_f32_e32 v103, v124, v125
	v_pk_mul_f32 v[96:97], v[96:97], v[112:113]
	v_mov_b64_e32 v[100:101], s[60:61]
	v_mul_f32_e32 v96, v96, v97
	v_cvt_pk_bf16_f32 v96, v96, v99
	v_cvt_pk_bf16_f32 v97, v98, v103
	v_cvt_pk_bf16_f32 v98, v121, v120
	v_cvt_pk_bf16_f32 v99, v102, v126
	v_ashrrev_i32_e32 v102, 4, v200
	v_mad_i64_i32 v[100:101], s[12:13], v102, s82, v[100:101]
	v_lshlrev_b64 v[100:101], 10, v[100:101]
	v_lshl_add_u64 v[100:101], s[36:37], 0, v[100:101]
	v_lshl_add_u64 v[100:101], v[100:101], 0, v[168:169]
	v_mov_b32_e32 v153, v169
	v_lshl_add_u64 v[100:101], v[100:101], 0, v[152:153]
	global_store_dwordx4 v[100:101], v[96:99], off
.LBB0_669:
	s_or_b64 exec, exec, s[62:63]
	s_nop 0
	v_fmamk_f32 v96, v201, 0x39800000, v191
	v_rsq_f32_e32 v96, v96
	v_and_b32_e32 v127, 0xfff, v198
	v_mul_f32_e32 v120, v92, v96
	v_mul_f32_e32 v121, v93, v96
	v_mul_f32_e32 v122, v94, v96
	v_mul_f32_e32 v123, v95, v96
	v_mul_f32_e32 v124, v88, v96
	v_mul_f32_e32 v125, v89, v96
	v_mul_f32_e32 v126, v90, v96
	v_mul_f32_e32 v97, v91, v96
	v_cmp_le_i32_e64 s[12:13], s53, v198
	v_cmp_gt_i32_e64 s[14:15], s86, v181
	v_cmp_gt_u32_e32 vcc, 2, v127
	v_mov_b32_dpp v89, v120 row_ror:1 row_mask:0xf bank_mask:0xf
	v_mov_b32_dpp v88, v120 row_ror:2 row_mask:0xf bank_mask:0xf
	v_mov_b32_dpp v91, v121 row_ror:1 row_mask:0xf bank_mask:0xf
	v_mov_b32_dpp v90, v121 row_ror:2 row_mask:0xf bank_mask:0xf
	v_mov_b32_dpp v93, v122 row_ror:1 row_mask:0xf bank_mask:0xf
	v_mov_b32_dpp v92, v122 row_ror:2 row_mask:0xf bank_mask:0xf
	v_mov_b32_dpp v95, v123 row_ror:1 row_mask:0xf bank_mask:0xf
	v_mov_b32_dpp v94, v123 row_ror:2 row_mask:0xf bank_mask:0xf
	v_mov_b32_dpp v99, v124 row_ror:1 row_mask:0xf bank_mask:0xf
	v_mov_b32_dpp v98, v124 row_ror:2 row_mask:0xf bank_mask:0xf
	v_mov_b32_dpp v101, v125 row_ror:1 row_mask:0xf bank_mask:0xf
	v_mov_b32_dpp v100, v125 row_ror:2 row_mask:0xf bank_mask:0xf
	v_mov_b32_dpp v103, v126 row_ror:1 row_mask:0xf bank_mask:0xf
	v_mov_b32_dpp v102, v126 row_ror:2 row_mask:0xf bank_mask:0xf
	v_mov_b32_dpp v113, v97 row_ror:1 row_mask:0xf bank_mask:0xf
	v_mov_b32_dpp v112, v97 row_ror:2 row_mask:0xf bank_mask:0xf
	s_and_b64 s[12:13], s[14:15], s[12:13]
	s_and_saveexec_b64 s[62:63], s[12:13]
	s_cbranch_execz .LBB0_671
	s_cmp_eq_u64 vcc, 0
	v_cndmask_b32_e64 v129, v113, v129, s[6:7]
	v_cmp_eq_u32_e64 s[14:15], 0, v127
	s_cselect_b64 s[12:13], -1, 0
	v_cndmask_b32_e64 v128, v112, v128, s[4:5]
	v_cndmask_b32_e64 v127, v129, 0, s[14:15]
	v_cndmask_b32_e64 v128, v128, 0, vcc
	v_fma_f32 v129, v79, v128, v75
	v_mov_b32_e32 v128, v71
	v_cndmask_b32_e64 v71, v103, v119, s[6:7]
	v_fmac_f32_e32 v129, v83, v127
	v_cndmask_b32_e64 v119, v71, 0, s[14:15]
	v_fmac_f32_e32 v129, v87, v97
	v_cndmask_b32_e64 v71, v102, v118, s[4:5]
	v_mul_f32_e32 v97, 0xbfb8aa3b, v129
	v_exp_f32_e32 v97, v97
	v_cndmask_b32_e64 v71, v71, 0, vcc
	v_fma_f32 v71, v78, v71, v74
	v_fmac_f32_e32 v71, v82, v119
	v_fmac_f32_e32 v71, v86, v126
	v_add_f32_e32 v97, 1.0, v97
	v_mul_f32_e32 v118, 0xbfb8aa3b, v71
	v_rcp_f32_e32 v97, v97
	v_exp_f32_e32 v126, v118
	v_cndmask_b32_e64 v117, v101, v117, s[6:7]
	v_cndmask_b32_e64 v116, v100, v116, s[4:5]
	v_pk_mul_f32 v[118:119], v[128:129], v[96:97]
	v_add_f32_e32 v97, 1.0, v126
	v_cndmask_b32_e64 v126, v117, 0, s[14:15]
	v_cndmask_b32_e64 v116, v116, 0, vcc
	v_fma_f32 v117, v77, v116, v73
	v_fmac_f32_e32 v117, v81, v126
	v_fmac_f32_e32 v117, v85, v125
	v_mul_f32_e32 v116, 0xbfb8aa3b, v117
	v_rcp_f32_e32 v97, v97
	v_exp_f32_e32 v116, v116
	v_cndmask_b32_e64 v111, v95, v111, s[6:7]
	v_cndmask_b32_e64 v110, v94, v110, s[4:5]
	v_pk_mul_f32 v[70:71], v[70:71], v[96:97]
	v_add_f32_e32 v97, 1.0, v116
	v_mov_b32_e32 v116, v69
	v_cndmask_b32_e64 v69, v99, v115, s[6:7]
	v_cndmask_b32_e64 v115, v69, 0, s[14:15]
	v_cndmask_b32_e64 v69, v98, v114, s[4:5]
	v_cndmask_b32_e64 v69, v69, 0, vcc
	v_rcp_f32_e32 v97, v97
	v_fma_f32 v69, v76, v69, v72
	v_fmac_f32_e32 v69, v80, v115
	v_fmac_f32_e32 v69, v84, v124
	v_mul_f32_e32 v114, 0xbfb8aa3b, v69
	v_exp_f32_e32 v124, v114
	v_pk_mul_f32 v[114:115], v[116:117], v[96:97]
	v_cndmask_b32_e64 v116, v111, 0, s[14:15]
	v_cndmask_b32_e64 v110, v110, 0, vcc
	v_fma_f32 v111, v59, v110, v55
	v_fmac_f32_e32 v111, v63, v116
	v_fmac_f32_e32 v111, v67, v123
	v_add_f32_e32 v97, 1.0, v124
	v_mul_f32_e32 v110, 0xbfb8aa3b, v111
	v_rcp_f32_e32 v97, v97
	v_exp_f32_e32 v110, v110
	v_cndmask_b32_e64 v107, v91, v107, s[6:7]
	v_cndmask_b32_e64 v106, v90, v106, s[4:5]
	v_pk_mul_f32 v[68:69], v[68:69], v[96:97]
	v_add_f32_e32 v97, 1.0, v110
	v_mov_b32_e32 v110, v51
	v_cndmask_b32_e64 v51, v93, v109, s[6:7]
	v_cndmask_b32_e64 v109, v51, 0, s[14:15]
	v_cndmask_b32_e64 v51, v92, v108, s[4:5]
	v_cndmask_b32_e64 v51, v51, 0, vcc
	v_rcp_f32_e32 v97, v97
	v_fma_f32 v51, v58, v51, v54
	v_fmac_f32_e32 v51, v62, v109
	v_fmac_f32_e32 v51, v66, v122
	v_mul_f32_e32 v108, 0xbfb8aa3b, v51
	v_exp_f32_e32 v116, v108
	v_pk_mul_f32 v[108:109], v[110:111], v[96:97]
	v_cndmask_b32_e64 v110, v107, 0, s[14:15]
	v_cndmask_b32_e64 v106, v106, 0, vcc
	v_fma_f32 v107, v57, v106, v53
	v_fmac_f32_e32 v107, v61, v110
	v_fmac_f32_e32 v107, v65, v121
	v_mul_f32_e32 v106, 0xbfb8aa3b, v107
	v_add_f32_e32 v97, 1.0, v116
	v_exp_f32_e32 v106, v106
	v_rcp_f32_e32 v97, v97
	v_mul_f32_e32 v70, v70, v71
	v_mul_f32_e32 v110, v118, v119
	v_add_f32_e32 v71, 1.0, v106
	v_mov_b32_e32 v106, v49
	v_cndmask_b32_e64 v49, v89, v105, s[6:7]
	v_pk_mul_f32 v[50:51], v[50:51], v[96:97]
	v_rcp_f32_e32 v97, v71
	v_cndmask_b32_e64 v71, v49, 0, s[14:15]
	v_cndmask_b32_e64 v49, v88, v104, s[4:5]
	v_cndmask_b32_e64 v49, v49, 0, vcc
	v_fma_f32 v49, v56, v49, v52
	v_fmac_f32_e32 v49, v60, v71
	v_fmac_f32_e32 v49, v64, v120
	v_mul_f32_e32 v71, 0xbfb8aa3b, v49
	v_exp_f32_e32 v71, v71
	v_mul_f32_e32 v105, v68, v69
	v_pk_mul_f32 v[68:69], v[106:107], v[96:97]
	v_mul_f32_e32 v50, v50, v51
	v_add_f32_e32 v71, 1.0, v71
	v_rcp_f32_e32 v97, v71
	v_mul_f32_e32 v51, v68, v69
	v_mul_f32_e32 v104, v114, v115
	v_mul_f32_e32 v71, v108, v109
	v_pk_mul_f32 v[48:49], v[48:49], v[96:97]
	v_mov_b64_e32 v[68:69], s[60:61]
	v_mul_f32_e32 v48, v48, v49
	v_cvt_pk_bf16_f32 v48, v48, v51
	v_cvt_pk_bf16_f32 v49, v50, v71
	v_cvt_pk_bf16_f32 v50, v105, v104
	v_cvt_pk_bf16_f32 v51, v70, v110
	v_ashrrev_i32_e32 v70, 4, v198
	v_mad_i64_i32 v[68:69], s[12:13], v70, s82, v[68:69]
	v_lshlrev_b64 v[68:69], 10, v[68:69]
	v_lshl_add_u64 v[68:69], s[36:37], 0, v[68:69]
	v_lshl_add_u64 v[68:69], v[68:69], 0, v[168:169]
	v_mov_b32_e32 v153, v169
	v_lshl_add_u64 v[68:69], v[68:69], 0, v[152:153]
	global_store_dwordx4 v[68:69], v[48:51], off
.LBB0_671:
	s_or_b64 exec, exec, s[62:63]
	s_nop 0
	v_fmamk_f32 v48, v199, 0x39800000, v191
	v_rsq_f32_e32 v48, v48
	v_and_b32_e32 v111, 0xfff, v196
	v_mul_f32_e32 v104, v44, v48
	v_mul_f32_e32 v105, v45, v48
	v_mul_f32_e32 v106, v46, v48
	v_mul_f32_e32 v107, v47, v48
	v_mul_f32_e32 v108, v40, v48
	v_mul_f32_e32 v109, v41, v48
	v_mul_f32_e32 v110, v42, v48
	v_mul_f32_e32 v49, v43, v48
	v_cmp_le_i32_e64 s[12:13], s53, v196
	v_cmp_gt_i32_e64 s[14:15], s87, v181
	v_cmp_gt_u32_e32 vcc, 2, v111
	v_mov_b32_dpp v41, v104 row_ror:1 row_mask:0xf bank_mask:0xf
	v_mov_b32_dpp v40, v104 row_ror:2 row_mask:0xf bank_mask:0xf
	v_mov_b32_dpp v43, v105 row_ror:1 row_mask:0xf bank_mask:0xf
	v_mov_b32_dpp v42, v105 row_ror:2 row_mask:0xf bank_mask:0xf
	v_mov_b32_dpp v45, v106 row_ror:1 row_mask:0xf bank_mask:0xf
	v_mov_b32_dpp v44, v106 row_ror:2 row_mask:0xf bank_mask:0xf
	v_mov_b32_dpp v47, v107 row_ror:1 row_mask:0xf bank_mask:0xf
	v_mov_b32_dpp v46, v107 row_ror:2 row_mask:0xf bank_mask:0xf
	v_mov_b32_dpp v51, v108 row_ror:1 row_mask:0xf bank_mask:0xf
	v_mov_b32_dpp v50, v108 row_ror:2 row_mask:0xf bank_mask:0xf
	v_mov_b32_dpp v69, v109 row_ror:1 row_mask:0xf bank_mask:0xf
	v_mov_b32_dpp v68, v109 row_ror:2 row_mask:0xf bank_mask:0xf
	v_mov_b32_dpp v71, v110 row_ror:1 row_mask:0xf bank_mask:0xf
	v_mov_b32_dpp v70, v110 row_ror:2 row_mask:0xf bank_mask:0xf
	v_mov_b32_dpp v97, v49 row_ror:1 row_mask:0xf bank_mask:0xf
	v_mov_b32_dpp v96, v49 row_ror:2 row_mask:0xf bank_mask:0xf
	s_and_b64 s[12:13], s[14:15], s[12:13]
	s_and_saveexec_b64 s[62:63], s[12:13]
	s_cbranch_execz .LBB0_673
	s_cmp_eq_u64 vcc, 0
	v_cndmask_b32_e64 v113, v97, v113, s[6:7]
	v_cmp_eq_u32_e64 s[14:15], 0, v111
	s_cselect_b64 s[12:13], -1, 0
	v_cndmask_b32_e64 v112, v96, v112, s[4:5]
	v_cndmask_b32_e64 v111, v113, 0, s[14:15]
	v_cndmask_b32_e64 v112, v112, 0, vcc
	v_fma_f32 v113, v79, v112, v75
	v_mov_b32_e32 v112, v39
	v_cndmask_b32_e64 v39, v71, v103, s[6:7]
	v_fmac_f32_e32 v113, v83, v111
	v_cndmask_b32_e64 v103, v39, 0, s[14:15]
	v_fmac_f32_e32 v113, v87, v49
	v_cndmask_b32_e64 v39, v70, v102, s[4:5]
	v_mul_f32_e32 v49, 0xbfb8aa3b, v113
	v_exp_f32_e32 v49, v49
	v_cndmask_b32_e64 v39, v39, 0, vcc
	v_fma_f32 v39, v78, v39, v74
	v_fmac_f32_e32 v39, v82, v103
	v_fmac_f32_e32 v39, v86, v110
	v_add_f32_e32 v49, 1.0, v49
	v_mul_f32_e32 v102, 0xbfb8aa3b, v39
	v_rcp_f32_e32 v49, v49
	v_exp_f32_e32 v110, v102
	v_cndmask_b32_e64 v101, v69, v101, s[6:7]
	v_cndmask_b32_e64 v100, v68, v100, s[4:5]
	v_pk_mul_f32 v[102:103], v[112:113], v[48:49]
	v_add_f32_e32 v49, 1.0, v110
	v_cndmask_b32_e64 v110, v101, 0, s[14:15]
	v_cndmask_b32_e64 v100, v100, 0, vcc
	v_fma_f32 v101, v77, v100, v73
	v_fmac_f32_e32 v101, v81, v110
	v_fmac_f32_e32 v101, v85, v109
	v_mul_f32_e32 v100, 0xbfb8aa3b, v101
	v_rcp_f32_e32 v49, v49
	v_exp_f32_e32 v100, v100
	v_cndmask_b32_e64 v95, v47, v95, s[6:7]
	v_cndmask_b32_e64 v94, v46, v94, s[4:5]
	v_pk_mul_f32 v[38:39], v[38:39], v[48:49]
	v_add_f32_e32 v49, 1.0, v100
	v_mov_b32_e32 v100, v37
	v_cndmask_b32_e64 v37, v51, v99, s[6:7]
	v_cndmask_b32_e64 v99, v37, 0, s[14:15]
	v_cndmask_b32_e64 v37, v50, v98, s[4:5]
	v_cndmask_b32_e64 v37, v37, 0, vcc
	v_rcp_f32_e32 v49, v49
	v_fma_f32 v37, v76, v37, v72
	v_fmac_f32_e32 v37, v80, v99
	v_fmac_f32_e32 v37, v84, v108
	v_mul_f32_e32 v98, 0xbfb8aa3b, v37
	v_exp_f32_e32 v108, v98
	v_pk_mul_f32 v[98:99], v[100:101], v[48:49]
	v_cndmask_b32_e64 v100, v95, 0, s[14:15]
	v_cndmask_b32_e64 v94, v94, 0, vcc
	v_fma_f32 v95, v59, v94, v55
	v_fmac_f32_e32 v95, v63, v100
	v_fmac_f32_e32 v95, v67, v107
	v_add_f32_e32 v49, 1.0, v108
	v_mul_f32_e32 v94, 0xbfb8aa3b, v95
	v_rcp_f32_e32 v49, v49
	v_exp_f32_e32 v94, v94
	v_cndmask_b32_e64 v91, v43, v91, s[6:7]
	v_cndmask_b32_e64 v90, v42, v90, s[4:5]
	v_pk_mul_f32 v[36:37], v[36:37], v[48:49]
	v_add_f32_e32 v49, 1.0, v94
	v_mov_b32_e32 v94, v35
	v_cndmask_b32_e64 v35, v45, v93, s[6:7]
	v_cndmask_b32_e64 v93, v35, 0, s[14:15]
	v_cndmask_b32_e64 v35, v44, v92, s[4:5]
	v_cndmask_b32_e64 v35, v35, 0, vcc
	v_rcp_f32_e32 v49, v49
	v_fma_f32 v35, v58, v35, v54
	v_fmac_f32_e32 v35, v62, v93
	v_fmac_f32_e32 v35, v66, v106
	v_mul_f32_e32 v92, 0xbfb8aa3b, v35
	v_exp_f32_e32 v100, v92
	v_pk_mul_f32 v[92:93], v[94:95], v[48:49]
	v_cndmask_b32_e64 v94, v91, 0, s[14:15]
	v_cndmask_b32_e64 v90, v90, 0, vcc
	v_fma_f32 v91, v57, v90, v53
	v_fmac_f32_e32 v91, v61, v94
	v_fmac_f32_e32 v91, v65, v105
	v_mul_f32_e32 v90, 0xbfb8aa3b, v91
	v_add_f32_e32 v49, 1.0, v100
	v_exp_f32_e32 v90, v90
	v_rcp_f32_e32 v49, v49
	v_mul_f32_e32 v38, v38, v39
	v_mul_f32_e32 v94, v102, v103
	v_add_f32_e32 v39, 1.0, v90
	v_mov_b32_e32 v90, v33
	v_cndmask_b32_e64 v33, v41, v89, s[6:7]
	v_pk_mul_f32 v[34:35], v[34:35], v[48:49]
	v_rcp_f32_e32 v49, v39
	v_cndmask_b32_e64 v39, v33, 0, s[14:15]
	v_cndmask_b32_e64 v33, v40, v88, s[4:5]
	v_cndmask_b32_e64 v33, v33, 0, vcc
	v_fma_f32 v33, v56, v33, v52
	v_fmac_f32_e32 v33, v60, v39
	v_fmac_f32_e32 v33, v64, v104
	v_mul_f32_e32 v39, 0xbfb8aa3b, v33
	v_exp_f32_e32 v39, v39
	v_mul_f32_e32 v89, v36, v37
	v_pk_mul_f32 v[36:37], v[90:91], v[48:49]
	v_mul_f32_e32 v34, v34, v35
	v_add_f32_e32 v39, 1.0, v39
	v_rcp_f32_e32 v49, v39
	v_mul_f32_e32 v35, v36, v37
	v_mul_f32_e32 v88, v98, v99
	v_mul_f32_e32 v39, v92, v93
	v_pk_mul_f32 v[32:33], v[32:33], v[48:49]
	v_mov_b64_e32 v[36:37], s[60:61]
	v_mul_f32_e32 v32, v32, v33
	v_cvt_pk_bf16_f32 v32, v32, v35
	v_cvt_pk_bf16_f32 v33, v34, v39
	v_cvt_pk_bf16_f32 v34, v89, v88
	v_cvt_pk_bf16_f32 v35, v38, v94
	v_ashrrev_i32_e32 v38, 4, v196
	v_mad_i64_i32 v[36:37], s[12:13], v38, s82, v[36:37]
	v_lshlrev_b64 v[36:37], 10, v[36:37]
	v_lshl_add_u64 v[36:37], s[36:37], 0, v[36:37]
	v_lshl_add_u64 v[36:37], v[36:37], 0, v[168:169]
	v_mov_b32_e32 v153, v169
	v_lshl_add_u64 v[36:37], v[36:37], 0, v[152:153]
	global_store_dwordx4 v[36:37], v[32:35], off
.LBB0_673:
	s_or_b64 exec, exec, s[62:63]
	s_nop 0
	v_fmamk_f32 v32, v197, 0x39800000, v191
	v_rsq_f32_e32 v32, v32
	v_and_b32_e32 v95, 0xfff, v194
	v_mul_f32_e32 v88, v28, v32
	v_mul_f32_e32 v89, v29, v32
	v_mul_f32_e32 v90, v30, v32
	v_mul_f32_e32 v91, v31, v32
	v_mul_f32_e32 v92, v24, v32
	v_mul_f32_e32 v93, v25, v32
	v_mul_f32_e32 v94, v26, v32
	v_mul_f32_e32 v33, v27, v32
	v_cmp_le_i32_e64 s[12:13], s53, v194
	v_cmp_gt_i32_e64 s[14:15], s88, v181
	v_cmp_gt_u32_e32 vcc, 2, v95
	v_mov_b32_dpp v25, v88 row_ror:1 row_mask:0xf bank_mask:0xf
	v_mov_b32_dpp v24, v88 row_ror:2 row_mask:0xf bank_mask:0xf
	v_mov_b32_dpp v27, v89 row_ror:1 row_mask:0xf bank_mask:0xf
	v_mov_b32_dpp v26, v89 row_ror:2 row_mask:0xf bank_mask:0xf
	v_mov_b32_dpp v29, v90 row_ror:1 row_mask:0xf bank_mask:0xf
	v_mov_b32_dpp v28, v90 row_ror:2 row_mask:0xf bank_mask:0xf
	v_mov_b32_dpp v31, v91 row_ror:1 row_mask:0xf bank_mask:0xf
	v_mov_b32_dpp v30, v91 row_ror:2 row_mask:0xf bank_mask:0xf
	v_mov_b32_dpp v35, v92 row_ror:1 row_mask:0xf bank_mask:0xf
	v_mov_b32_dpp v34, v92 row_ror:2 row_mask:0xf bank_mask:0xf
	v_mov_b32_dpp v37, v93 row_ror:1 row_mask:0xf bank_mask:0xf
	v_mov_b32_dpp v36, v93 row_ror:2 row_mask:0xf bank_mask:0xf
	v_mov_b32_dpp v39, v94 row_ror:1 row_mask:0xf bank_mask:0xf
	v_mov_b32_dpp v38, v94 row_ror:2 row_mask:0xf bank_mask:0xf
	v_mov_b32_dpp v49, v33 row_ror:1 row_mask:0xf bank_mask:0xf
	v_mov_b32_dpp v48, v33 row_ror:2 row_mask:0xf bank_mask:0xf
	s_and_b64 s[12:13], s[14:15], s[12:13]
	s_and_saveexec_b64 s[62:63], s[12:13]
	s_cbranch_execz .LBB0_675
	s_cmp_eq_u64 vcc, 0
	v_cndmask_b32_e64 v97, v49, v97, s[6:7]
	v_cmp_eq_u32_e64 s[14:15], 0, v95
	s_cselect_b64 s[12:13], -1, 0
	v_cndmask_b32_e64 v96, v48, v96, s[4:5]
	v_cndmask_b32_e64 v95, v97, 0, s[14:15]
	v_cndmask_b32_e64 v96, v96, 0, vcc
	v_fma_f32 v97, v79, v96, v75
	v_mov_b32_e32 v96, v23
	v_cndmask_b32_e64 v23, v39, v71, s[6:7]
	v_fmac_f32_e32 v97, v83, v95
	v_cndmask_b32_e64 v71, v23, 0, s[14:15]
	v_fmac_f32_e32 v97, v87, v33
	v_cndmask_b32_e64 v23, v38, v70, s[4:5]
	v_mul_f32_e32 v33, 0xbfb8aa3b, v97
	v_exp_f32_e32 v33, v33
	v_cndmask_b32_e64 v23, v23, 0, vcc
	v_fma_f32 v23, v78, v23, v74
	v_fmac_f32_e32 v23, v82, v71
	v_fmac_f32_e32 v23, v86, v94
	v_add_f32_e32 v33, 1.0, v33
	v_mul_f32_e32 v70, 0xbfb8aa3b, v23
	v_rcp_f32_e32 v33, v33
	v_exp_f32_e32 v94, v70
	v_cndmask_b32_e64 v69, v37, v69, s[6:7]
	v_cndmask_b32_e64 v68, v36, v68, s[4:5]
	v_pk_mul_f32 v[70:71], v[96:97], v[32:33]
	v_add_f32_e32 v33, 1.0, v94
	v_cndmask_b32_e64 v94, v69, 0, s[14:15]
	v_cndmask_b32_e64 v68, v68, 0, vcc
	v_fma_f32 v69, v77, v68, v73
	v_fmac_f32_e32 v69, v81, v94
	v_fmac_f32_e32 v69, v85, v93
	v_mul_f32_e32 v68, 0xbfb8aa3b, v69
	v_rcp_f32_e32 v33, v33
	v_exp_f32_e32 v68, v68
	v_cndmask_b32_e64 v47, v31, v47, s[6:7]
	v_cndmask_b32_e64 v46, v30, v46, s[4:5]
	v_pk_mul_f32 v[22:23], v[22:23], v[32:33]
	v_add_f32_e32 v33, 1.0, v68
	v_mov_b32_e32 v68, v21
	v_cndmask_b32_e64 v21, v35, v51, s[6:7]
	v_cndmask_b32_e64 v51, v21, 0, s[14:15]
	v_cndmask_b32_e64 v21, v34, v50, s[4:5]
	v_cndmask_b32_e64 v21, v21, 0, vcc
	v_rcp_f32_e32 v33, v33
	v_fma_f32 v21, v76, v21, v72
	v_fmac_f32_e32 v21, v80, v51
	v_fmac_f32_e32 v21, v84, v92
	v_mul_f32_e32 v50, 0xbfb8aa3b, v21
	v_exp_f32_e32 v92, v50
	v_pk_mul_f32 v[50:51], v[68:69], v[32:33]
	v_cndmask_b32_e64 v68, v47, 0, s[14:15]
	v_cndmask_b32_e64 v46, v46, 0, vcc
	v_fma_f32 v47, v59, v46, v55
	v_fmac_f32_e32 v47, v63, v68
	v_fmac_f32_e32 v47, v67, v91
	v_add_f32_e32 v33, 1.0, v92
	v_mul_f32_e32 v46, 0xbfb8aa3b, v47
	v_rcp_f32_e32 v33, v33
	v_exp_f32_e32 v46, v46
	v_cndmask_b32_e64 v43, v27, v43, s[6:7]
	v_cndmask_b32_e64 v42, v26, v42, s[4:5]
	v_pk_mul_f32 v[20:21], v[20:21], v[32:33]
	v_add_f32_e32 v33, 1.0, v46
	v_mov_b32_e32 v46, v19
	v_cndmask_b32_e64 v19, v29, v45, s[6:7]
	v_cndmask_b32_e64 v45, v19, 0, s[14:15]
	v_cndmask_b32_e64 v19, v28, v44, s[4:5]
	v_cndmask_b32_e64 v19, v19, 0, vcc
	v_rcp_f32_e32 v33, v33
	v_fma_f32 v19, v58, v19, v54
	v_fmac_f32_e32 v19, v62, v45
	v_fmac_f32_e32 v19, v66, v90
	v_mul_f32_e32 v44, 0xbfb8aa3b, v19
	v_exp_f32_e32 v68, v44
	v_pk_mul_f32 v[44:45], v[46:47], v[32:33]
	v_cndmask_b32_e64 v46, v43, 0, s[14:15]
	v_cndmask_b32_e64 v42, v42, 0, vcc
	v_fma_f32 v43, v57, v42, v53
	v_fmac_f32_e32 v43, v61, v46
	v_fmac_f32_e32 v43, v65, v89
	v_mul_f32_e32 v42, 0xbfb8aa3b, v43
	v_add_f32_e32 v33, 1.0, v68
	v_exp_f32_e32 v42, v42
	v_rcp_f32_e32 v33, v33
	v_mul_f32_e32 v22, v22, v23
	v_mul_f32_e32 v46, v70, v71
	v_add_f32_e32 v23, 1.0, v42
	v_mov_b32_e32 v42, v17
	v_cndmask_b32_e64 v17, v25, v41, s[6:7]
	v_pk_mul_f32 v[18:19], v[18:19], v[32:33]
	v_rcp_f32_e32 v33, v23
	v_cndmask_b32_e64 v23, v17, 0, s[14:15]
	v_cndmask_b32_e64 v17, v24, v40, s[4:5]
	v_cndmask_b32_e64 v17, v17, 0, vcc
	v_fma_f32 v17, v56, v17, v52
	v_fmac_f32_e32 v17, v60, v23
	v_fmac_f32_e32 v17, v64, v88
	v_mul_f32_e32 v23, 0xbfb8aa3b, v17
	v_exp_f32_e32 v23, v23
	v_mul_f32_e32 v41, v20, v21
	v_pk_mul_f32 v[20:21], v[42:43], v[32:33]
	v_mul_f32_e32 v18, v18, v19
	v_add_f32_e32 v23, 1.0, v23
	v_rcp_f32_e32 v33, v23
	v_mul_f32_e32 v19, v20, v21
	v_mul_f32_e32 v40, v50, v51
	v_mul_f32_e32 v23, v44, v45
	v_pk_mul_f32 v[16:17], v[16:17], v[32:33]
	v_mov_b64_e32 v[20:21], s[60:61]
	v_mul_f32_e32 v16, v16, v17
	v_cvt_pk_bf16_f32 v16, v16, v19
	v_cvt_pk_bf16_f32 v17, v18, v23
	v_cvt_pk_bf16_f32 v18, v41, v40
	v_cvt_pk_bf16_f32 v19, v22, v46
	v_ashrrev_i32_e32 v22, 4, v194
	v_mad_i64_i32 v[20:21], s[12:13], v22, s82, v[20:21]
	v_lshlrev_b64 v[20:21], 10, v[20:21]
	v_lshl_add_u64 v[20:21], s[36:37], 0, v[20:21]
	v_lshl_add_u64 v[20:21], v[20:21], 0, v[168:169]
	v_mov_b32_e32 v153, v169
	v_lshl_add_u64 v[20:21], v[20:21], 0, v[152:153]
	global_store_dwordx4 v[20:21], v[16:19], off
.LBB0_675:
	s_or_b64 exec, exec, s[62:63]
	v_mul_f32_e32 v12, v12, v180
	v_mul_f32_e32 v13, v13, v180
	v_mul_f32_e32 v14, v14, v180
	v_mul_f32_e32 v16, v15, v180
	v_mul_f32_e32 v18, v8, v180
	v_mul_f32_e32 v21, v9, v180
	v_mul_f32_e32 v32, v10, v180
	v_mul_f32_e32 v41, v11, v180
	v_and_b32_e32 v42, 0xfff, v193
	v_cmp_le_i32_e64 s[12:13], s53, v193
	v_cmp_gt_i32_e64 s[14:15], s89, v181
	v_cmp_gt_u32_e32 vcc, 2, v42
	v_mov_b32_dpp v9, v12 row_ror:1 row_mask:0xf bank_mask:0xf
	v_mov_b32_dpp v8, v12 row_ror:2 row_mask:0xf bank_mask:0xf
	v_mov_b32_dpp v11, v13 row_ror:1 row_mask:0xf bank_mask:0xf
	v_mov_b32_dpp v10, v13 row_ror:2 row_mask:0xf bank_mask:0xf
	v_mov_b32_dpp v17, v14 row_ror:1 row_mask:0xf bank_mask:0xf
	v_mov_b32_dpp v15, v14 row_ror:2 row_mask:0xf bank_mask:0xf
	v_mov_b32_dpp v20, v16 row_ror:1 row_mask:0xf bank_mask:0xf
	v_mov_b32_dpp v19, v16 row_ror:2 row_mask:0xf bank_mask:0xf
	v_mov_b32_dpp v23, v18 row_ror:1 row_mask:0xf bank_mask:0xf
	v_mov_b32_dpp v22, v18 row_ror:2 row_mask:0xf bank_mask:0xf
	v_mov_b32_dpp v40, v21 row_ror:1 row_mask:0xf bank_mask:0xf
	v_mov_b32_dpp v33, v21 row_ror:2 row_mask:0xf bank_mask:0xf
	v_mov_b32_dpp v44, v32 row_ror:1 row_mask:0xf bank_mask:0xf
	v_mov_b32_dpp v43, v32 row_ror:2 row_mask:0xf bank_mask:0xf
	v_mov_b32_dpp v46, v41 row_ror:1 row_mask:0xf bank_mask:0xf
	v_mov_b32_dpp v45, v41 row_ror:2 row_mask:0xf bank_mask:0xf
	s_and_b64 s[12:13], s[14:15], s[12:13]
	s_and_saveexec_b64 s[62:63], s[12:13]
	s_cbranch_execz .LBB0_677
	s_cmp_eq_u64 vcc, 0
	v_cndmask_b32_e64 v46, v46, v49, s[6:7]
	v_cmp_eq_u32_e64 s[14:15], 0, v42
	s_cselect_b64 s[12:13], -1, 0
	v_cndmask_b32_e64 v45, v45, v48, s[4:5]
	v_cndmask_b32_e64 v42, v46, 0, s[14:15]
	v_cndmask_b32_e64 v45, v45, 0, vcc
	v_mov_b32_e32 v46, v7
	v_cndmask_b32_e64 v7, v44, v39, s[6:7]
	v_fma_f32 v47, v79, v45, v75
	v_cndmask_b32_e64 v39, v7, 0, s[14:15]
	v_fmac_f32_e32 v47, v83, v42
	v_cndmask_b32_e64 v7, v43, v38, s[4:5]
	v_fmac_f32_e32 v47, v87, v41
	v_mul_f32_e32 v41, 0xbfb8aa3b, v47
	v_cndmask_b32_e64 v7, v7, 0, vcc
	v_exp_f32_e32 v41, v41
	v_fma_f32 v7, v78, v7, v74
	v_fmac_f32_e32 v7, v82, v39
	v_fmac_f32_e32 v7, v86, v32
	v_mul_f32_e32 v32, 0xbfb8aa3b, v7
	v_add_f32_e32 v41, 1.0, v41
	v_exp_f32_e32 v32, v32
	v_rcp_f32_e32 v181, v41
	v_cndmask_b32_e64 v33, v33, v36, s[4:5]
	v_add_f32_e32 v32, 1.0, v32
	v_pk_mul_f32 v[38:39], v[46:47], v[180:181]
	v_rcp_f32_e32 v181, v32
	v_cndmask_b32_e64 v32, v40, v37, s[6:7]
	v_cndmask_b32_e64 v33, v33, 0, vcc
	v_cndmask_b32_e64 v32, v32, 0, s[14:15]
	v_fma_f32 v33, v77, v33, v73
	v_fmac_f32_e32 v33, v81, v32
	v_fmac_f32_e32 v33, v85, v21
	v_mul_f32_e32 v21, 0xbfb8aa3b, v33
	v_exp_f32_e32 v21, v21
	v_pk_mul_f32 v[6:7], v[6:7], v[180:181]
	v_cndmask_b32_e64 v22, v22, v34, s[4:5]
	v_mov_b32_e32 v32, v5
	v_add_f32_e32 v21, 1.0, v21
	v_rcp_f32_e32 v181, v21
	v_cndmask_b32_e64 v21, v23, v35, s[6:7]
	v_cndmask_b32_e64 v21, v21, 0, s[14:15]
	v_cndmask_b32_e64 v22, v22, 0, vcc
	v_fmac_f32_e32 v72, v76, v22
	v_fmac_f32_e32 v72, v80, v21
	v_fmac_f32_e32 v72, v84, v18
	v_mul_f32_e32 v18, 0xbfb8aa3b, v72
	v_exp_f32_e32 v18, v18
	v_pk_mul_f32 v[22:23], v[32:33], v[180:181]
	v_cndmask_b32_e64 v11, v11, v27, s[6:7]
	v_cndmask_b32_e64 v10, v10, v26, s[4:5]
	v_add_f32_e32 v5, 1.0, v18
	v_rcp_f32_e32 v181, v5
	v_cndmask_b32_e64 v5, v20, v31, s[6:7]
	v_cndmask_b32_e64 v5, v5, 0, s[14:15]
	v_cndmask_b32_e64 v18, v19, v30, s[4:5]
	v_cndmask_b32_e64 v18, v18, 0, vcc
	v_fma_f32 v19, v59, v18, v55
	v_fmac_f32_e32 v19, v63, v5
	v_fmac_f32_e32 v19, v67, v16
	v_mul_f32_e32 v5, 0xbfb8aa3b, v19
	v_exp_f32_e32 v16, v5
	v_mov_b32_e32 v5, v72
	v_mov_b32_e32 v18, v3
	v_cndmask_b32_e64 v3, v17, v29, s[6:7]
	v_add_f32_e32 v16, 1.0, v16
	v_pk_mul_f32 v[4:5], v[4:5], v[180:181]
	v_rcp_f32_e32 v181, v16
	v_cndmask_b32_e64 v16, v3, 0, s[14:15]
	v_cndmask_b32_e64 v3, v15, v28, s[4:5]
	v_cndmask_b32_e64 v3, v3, 0, vcc
	v_fma_f32 v3, v58, v3, v54
	v_fmac_f32_e32 v3, v62, v16
	v_fmac_f32_e32 v3, v66, v14
	v_mul_f32_e32 v14, 0xbfb8aa3b, v3
	v_exp_f32_e32 v14, v14
	v_mul_f32_e32 v16, v6, v7
	v_pk_mul_f32 v[6:7], v[18:19], v[180:181]
	v_mov_b32_e32 v153, v169
	v_add_f32_e32 v14, 1.0, v14
	v_rcp_f32_e32 v181, v14
	v_cndmask_b32_e64 v14, v11, 0, s[14:15]
	v_cndmask_b32_e64 v10, v10, 0, vcc
	v_fma_f32 v11, v57, v10, v53
	v_fmac_f32_e32 v11, v61, v14
	v_fmac_f32_e32 v11, v65, v13
	v_mul_f32_e32 v10, 0xbfb8aa3b, v11
	v_exp_f32_e32 v10, v10
	v_mul_f32_e32 v14, v4, v5
	v_pk_mul_f32 v[2:3], v[2:3], v[180:181]
	v_mul_f32_e32 v6, v6, v7
	v_add_f32_e32 v4, 1.0, v10
	v_rcp_f32_e32 v181, v4
	v_cndmask_b32_e64 v4, v9, v25, s[6:7]
	v_cndmask_b32_e64 v4, v4, 0, s[14:15]
	v_cndmask_b32_e64 v5, v8, v24, s[4:5]
	v_cndmask_b32_e64 v5, v5, 0, vcc
	v_fmac_f32_e32 v52, v56, v5
	v_fmac_f32_e32 v52, v60, v4
	v_fmac_f32_e32 v52, v64, v12
	v_mul_f32_e32 v4, 0xbfb8aa3b, v52
	v_exp_f32_e32 v8, v4
	v_mov_b32_e32 v10, v1
	v_pk_mul_f32 v[4:5], v[10:11], v[180:181]
	v_mul_f32_e32 v2, v2, v3
	v_add_f32_e32 v1, 1.0, v8
	v_rcp_f32_e32 v181, v1
	v_mov_b32_e32 v1, v52
	v_mul_f32_e32 v3, v4, v5
	v_mov_b64_e32 v[4:5], s[60:61]
	v_pk_mul_f32 v[0:1], v[0:1], v[180:181]
	v_mul_f32_e32 v15, v38, v39
	v_mul_f32_e32 v0, v0, v1
	v_cvt_pk_bf16_f32 v0, v0, v3
	v_cvt_pk_bf16_f32 v1, v2, v6
	v_ashrrev_i32_e32 v6, 4, v193
	v_mad_i64_i32 v[4:5], s[12:13], v6, s82, v[4:5]
	v_lshlrev_b64 v[4:5], 10, v[4:5]
	v_lshl_add_u64 v[4:5], s[36:37], 0, v[4:5]
	v_lshl_add_u64 v[4:5], v[4:5], 0, v[168:169]
	v_lshl_add_u64 v[4:5], v[4:5], 0, v[152:153]
	v_mul_f32_e32 v13, v22, v23
	v_cvt_pk_bf16_f32 v2, v14, v13
	v_cvt_pk_bf16_f32 v3, v16, v15
	global_store_dwordx4 v[4:5], v[0:3], off
